# stagger two workgroup groups by 2us at P1 start
# baseline (speedup 1.0000x reference)
; #define REPS(k) for (int rep = 0; rep < ((DUP_PHASE == (k)) ? 2 : 1); ++rep)
; __global__ void __launch_bounds__(NT, 2) fwd(Args args) {
;     ...
;     bf16 *WT_IN = (bf16*)(ws + WS_WIN), *WT_OUT = (bf16*)(ws + WS_WOUT), *AH = (bf16*)(ws + WS_AH), *CB = (bf16*)(ws + WS_CB), *UB = (bf16*)(ws + WS_U),
;          *QB = (bf16*)(ws + WS_Q), *KB = (bf16*)(ws + WS_K), *VB = (bf16*)(ws + WS_V), *MQB = (bf16*)(ws + WS_MQ), *GB = (bf16*)(ws + WS_G),
;          *MKB = (bf16*)(ws + WS_MK), *MVB = (bf16*)(ws + WS_MV), *OC = (bf16*)(ws + WS_OC), *MIX = (bf16*)(ws + WS_MIX);
;     ...
;     if (IN(1)) REPS(1) {
;         pg8::Gemm g{AH, WT_IN, MA, NBT, D}; SchedIn S{G, bx, (unsigned*)(ctl + CW_EA), bar.x, bar.st};
;         EpiIn E{CB, UB, QB, KB, VB, MQB, GB, MKB, MVB, out};
;         pg8::gemm_phase<EpiIn, SchedIn, true, true>(lds, g, S, E);
.LBB0_162:
	s_waitcnt lgkmcnt(0)
	v_writelane_b32 v247, s36, 25
	s_mov_b64 s[0:1], s[52:53]
	s_mov_b32 s2, s54
	v_writelane_b32 v247, s37, 26
	v_writelane_b32 v247, s38, 27
	v_writelane_b32 v247, s39, 28
	v_writelane_b32 v247, s40, 29
	v_writelane_b32 v247, s41, 30
	v_writelane_b32 v247, s42, 31
	v_writelane_b32 v247, s43, 32
	v_writelane_b32 v247, s44, 33
	v_writelane_b32 v247, s45, 34
	v_writelane_b32 v247, s46, 35
	v_writelane_b32 v247, s47, 36
	v_writelane_b32 v247, s48, 37
	v_writelane_b32 v247, s49, 38
	v_writelane_b32 v247, s50, 39
	v_writelane_b32 v247, s51, 40
	v_writelane_b32 v247, s0, 41
	s_cmp_lt_i32 s52, 2
	s_cselect_b64 s[12:13], -1, 0
	v_writelane_b32 v247, s1, 42
	v_writelane_b32 v247, s2, 43
	v_writelane_b32 v247, s3, 44
	s_add_u32 s0, s82, 0x3400000
	s_addc_u32 s1, s83, 0
	s_add_u32 s76, s82, 0x5a00000
	s_addc_u32 s77, s83, 0
	s_add_u32 s60, s82, 0x7e00000
	s_addc_u32 s61, s83, 0
	s_add_u32 s64, s82, 0xaa00000
	s_addc_u32 s65, s83, 0
	s_add_u32 s36, s82, 0xe000000
	s_addc_u32 s37, s83, 0
	s_add_u32 s62, s82, 0x3e00000
	v_writelane_b32 v247, s0, 45
	s_addc_u32 s63, s83, 0
	s_add_u32 s78, s82, 0x4800000
	v_writelane_b32 v247, s1, 46
	s_addc_u32 s79, s83, 0
	v_writelane_b32 v247, s96, 47
	s_add_u32 s80, s82, 0x6c00000
	v_writelane_b32 v247, s97, 48
	s_addc_u32 s81, s83, 0
	v_writelane_b32 v247, s58, 49
	s_add_u32 s24, s82, 0x8800000
	s_addc_u32 s25, s83, 0
	v_writelane_b32 v247, s59, 50
	v_writelane_b32 v247, s60, 51
	s_add_u32 s66, s82, 0xab00000
	s_addc_u32 s67, s83, 0
	v_writelane_b32 v247, s61, 52
	s_and_b64 s[70:71], s[12:13], s[4:5]
	v_writelane_b32 v247, s65, 53
	s_andn2_b64 vcc, exec, s[70:71]
	v_writelane_b32 v247, s66, 54
	v_writelane_b32 v247, s67, 55
	s_cbranch_vccnz .LBB0_536
	s_lshr_b32 s40, s96, 3
	s_and_b32 s40, s40, 1
.Lstag:
	s_cmp_eq_u32 s40, 0
	s_cbranch_scc1 .Lstag_done
	s_sleep 64
	s_sub_u32 s40, s40, 1
	s_branch .Lstag
